# P2 w_in fast epilogue: non-temporal (nt) hint on the 64 tile stores so the streamed ACT output does not evict A/B tiles from L2
# speedup vs baseline: 1.0744x; 1.0185x over previous
.Lfe_fast:
	s_cmp_gt_i32 s33, 7
	s_cbranch_scc1 .Lfe_gf
	s_lshl_b32 s9, s10, 8
	s_add_i32 s9, s9, s86
	s_mul_i32 s11, s9, 0x2080
	s_lshl_b32 s12, s8, 9
	s_add_i32 s11, s11, s12
	s_lshl_b32 s12, s87, 1
	s_add_i32 s11, s11, s12
	s_add_u32 s12, s18, s11
	s_addc_u32 s13, s19, 0
	v_mul_u32_u24_e32 v240, 0x2080, v176
	v_lshl_add_u32 v240, v177, 4, v240
	s_cmp_eq_u32 s33, 2
	s_cbranch_scc1 .Lfe_act_q
	s_cmp_eq_u32 s33, 5
	s_cbranch_scc1 .Lfe_act_q
	v_cvt_pk_bf16_f32 v124, v124, v125
	v_cvt_pk_bf16_f32 v125, v126, v127
	v_cvt_pk_bf16_f32 v126, v120, v121
	v_cvt_pk_bf16_f32 v127, v122, v123
	global_store_dwordx4 v240, v[124:127], s[12:13] nt
	v_cvt_pk_bf16_f32 v116, v116, v117
	v_cvt_pk_bf16_f32 v117, v118, v119
	v_cvt_pk_bf16_f32 v118, v112, v113
	v_cvt_pk_bf16_f32 v119, v114, v115
	global_store_dwordx4 v240, v[116:119], s[12:13] offset:256 nt
	s_add_u32 s12, s12, 0x20800
	s_addc_u32 s13, s13, 0
	v_cvt_pk_bf16_f32 v108, v108, v109
	v_cvt_pk_bf16_f32 v109, v110, v111
	v_cvt_pk_bf16_f32 v110, v104, v105
	v_cvt_pk_bf16_f32 v111, v106, v107
	global_store_dwordx4 v240, v[108:111], s[12:13] nt
	v_cvt_pk_bf16_f32 v100, v100, v101
	v_cvt_pk_bf16_f32 v101, v102, v103
	v_cvt_pk_bf16_f32 v102, v96, v97
	v_cvt_pk_bf16_f32 v103, v98, v99
	global_store_dwordx4 v240, v[100:103], s[12:13] offset:256 nt
	s_add_u32 s12, s12, 0x20800
	s_addc_u32 s13, s13, 0
	v_cvt_pk_bf16_f32 v92, v92, v93
	v_cvt_pk_bf16_f32 v93, v94, v95
	v_cvt_pk_bf16_f32 v94, v88, v89
	v_cvt_pk_bf16_f32 v95, v90, v91
	global_store_dwordx4 v240, v[92:95], s[12:13] nt
	v_cvt_pk_bf16_f32 v84, v84, v85
	v_cvt_pk_bf16_f32 v85, v86, v87
	v_cvt_pk_bf16_f32 v86, v80, v81
	v_cvt_pk_bf16_f32 v87, v82, v83
	global_store_dwordx4 v240, v[84:87], s[12:13] offset:256 nt
	s_add_u32 s12, s12, 0x20800
	s_addc_u32 s13, s13, 0
	v_cvt_pk_bf16_f32 v76, v76, v77
	v_cvt_pk_bf16_f32 v77, v78, v79
	v_cvt_pk_bf16_f32 v78, v72, v73
	v_cvt_pk_bf16_f32 v79, v74, v75
	global_store_dwordx4 v240, v[76:79], s[12:13] nt
	v_cvt_pk_bf16_f32 v68, v68, v69
	v_cvt_pk_bf16_f32 v69, v70, v71
	v_cvt_pk_bf16_f32 v70, v64, v65
	v_cvt_pk_bf16_f32 v71, v66, v67
	global_store_dwordx4 v240, v[68:71], s[12:13] offset:256 nt
	s_add_u32 s12, s12, 0xa2800
	s_addc_u32 s13, s13, 0
	v_cvt_pk_bf16_f32 v60, v60, v61
	v_cvt_pk_bf16_f32 v61, v62, v63
	v_cvt_pk_bf16_f32 v62, v56, v57
	v_cvt_pk_bf16_f32 v63, v58, v59
	global_store_dwordx4 v240, v[60:63], s[12:13] nt
	v_cvt_pk_bf16_f32 v52, v52, v53
	v_cvt_pk_bf16_f32 v53, v54, v55
	v_cvt_pk_bf16_f32 v54, v48, v49
	v_cvt_pk_bf16_f32 v55, v50, v51
	global_store_dwordx4 v240, v[52:55], s[12:13] offset:256 nt
	s_add_u32 s12, s12, 0x20800
	s_addc_u32 s13, s13, 0
	v_cvt_pk_bf16_f32 v44, v44, v45
	v_cvt_pk_bf16_f32 v45, v46, v47
	v_cvt_pk_bf16_f32 v46, v40, v41
	v_cvt_pk_bf16_f32 v47, v42, v43
	global_store_dwordx4 v240, v[44:47], s[12:13] nt
	v_cvt_pk_bf16_f32 v36, v36, v37
	v_cvt_pk_bf16_f32 v37, v38, v39
	v_cvt_pk_bf16_f32 v38, v32, v33
	v_cvt_pk_bf16_f32 v39, v34, v35
	global_store_dwordx4 v240, v[36:39], s[12:13] offset:256 nt
	s_add_u32 s12, s12, 0x20800
	s_addc_u32 s13, s13, 0
	v_cvt_pk_bf16_f32 v28, v28, v29
	v_cvt_pk_bf16_f32 v29, v30, v31
	v_cvt_pk_bf16_f32 v30, v24, v25
	v_cvt_pk_bf16_f32 v31, v26, v27
	global_store_dwordx4 v240, v[28:31], s[12:13] nt
	v_cvt_pk_bf16_f32 v20, v20, v21
	v_cvt_pk_bf16_f32 v21, v22, v23
	v_cvt_pk_bf16_f32 v22, v16, v17
	v_cvt_pk_bf16_f32 v23, v18, v19
	global_store_dwordx4 v240, v[20:23], s[12:13] offset:256 nt
	s_add_u32 s12, s12, 0x20800
	s_addc_u32 s13, s13, 0
	v_cvt_pk_bf16_f32 v12, v12, v13
	v_cvt_pk_bf16_f32 v13, v14, v15
	v_cvt_pk_bf16_f32 v14, v8, v9
	v_cvt_pk_bf16_f32 v15, v10, v11
	global_store_dwordx4 v240, v[12:15], s[12:13] nt
	v_cvt_pk_bf16_f32 v4, v4, v5
	v_cvt_pk_bf16_f32 v5, v6, v7
	v_cvt_pk_bf16_f32 v6, v0, v1
	v_cvt_pk_bf16_f32 v7, v2, v3
	global_store_dwordx4 v240, v[4:7], s[12:13] offset:256 nt
	s_branch .Lfe_join
.Lfe_act_q:
	v_mul_f32_e32 v124, s78, v124
	v_mul_f32_e32 v125, s78, v125
	v_mul_f32_e32 v126, s78, v126
	v_mul_f32_e32 v127, s78, v127
	v_mul_f32_e32 v120, s78, v120
	v_mul_f32_e32 v121, s78, v121
	v_mul_f32_e32 v122, s78, v122
	v_mul_f32_e32 v123, s78, v123
	v_cvt_pk_bf16_f32 v124, v124, v125
	v_cvt_pk_bf16_f32 v125, v126, v127
	v_cvt_pk_bf16_f32 v126, v120, v121
	v_cvt_pk_bf16_f32 v127, v122, v123
	global_store_dwordx4 v240, v[124:127], s[12:13] nt
	v_mul_f32_e32 v116, s78, v116
	v_mul_f32_e32 v117, s78, v117
	v_mul_f32_e32 v118, s78, v118
	v_mul_f32_e32 v119, s78, v119
	v_mul_f32_e32 v112, s78, v112
	v_mul_f32_e32 v113, s78, v113
	v_mul_f32_e32 v114, s78, v114
	v_mul_f32_e32 v115, s78, v115
	v_cvt_pk_bf16_f32 v116, v116, v117
	v_cvt_pk_bf16_f32 v117, v118, v119
	v_cvt_pk_bf16_f32 v118, v112, v113
	v_cvt_pk_bf16_f32 v119, v114, v115
	global_store_dwordx4 v240, v[116:119], s[12:13] offset:256 nt
	s_add_u32 s12, s12, 0x20800
	s_addc_u32 s13, s13, 0
	v_mul_f32_e32 v108, s78, v108
	v_mul_f32_e32 v109, s78, v109
	v_mul_f32_e32 v110, s78, v110
	v_mul_f32_e32 v111, s78, v111
	v_mul_f32_e32 v104, s78, v104
	v_mul_f32_e32 v105, s78, v105
	v_mul_f32_e32 v106, s78, v106
	v_mul_f32_e32 v107, s78, v107
	v_cvt_pk_bf16_f32 v108, v108, v109
	v_cvt_pk_bf16_f32 v109, v110, v111
	v_cvt_pk_bf16_f32 v110, v104, v105
	v_cvt_pk_bf16_f32 v111, v106, v107
	global_store_dwordx4 v240, v[108:111], s[12:13] nt
	v_mul_f32_e32 v100, s78, v100
	v_mul_f32_e32 v101, s78, v101
	v_mul_f32_e32 v102, s78, v102
	v_mul_f32_e32 v103, s78, v103
	v_mul_f32_e32 v96, s78, v96
	v_mul_f32_e32 v97, s78, v97
	v_mul_f32_e32 v98, s78, v98
	v_mul_f32_e32 v99, s78, v99
	v_cvt_pk_bf16_f32 v100, v100, v101
	v_cvt_pk_bf16_f32 v101, v102, v103
	v_cvt_pk_bf16_f32 v102, v96, v97
	v_cvt_pk_bf16_f32 v103, v98, v99
	global_store_dwordx4 v240, v[100:103], s[12:13] offset:256 nt
	s_add_u32 s12, s12, 0x20800
	s_addc_u32 s13, s13, 0
	v_mul_f32_e32 v92, s78, v92
	v_mul_f32_e32 v93, s78, v93
	v_mul_f32_e32 v94, s78, v94
	v_mul_f32_e32 v95, s78, v95
	v_mul_f32_e32 v88, s78, v88
	v_mul_f32_e32 v89, s78, v89
	v_mul_f32_e32 v90, s78, v90
	v_mul_f32_e32 v91, s78, v91
	v_cvt_pk_bf16_f32 v92, v92, v93
	v_cvt_pk_bf16_f32 v93, v94, v95
	v_cvt_pk_bf16_f32 v94, v88, v89
	v_cvt_pk_bf16_f32 v95, v90, v91
	global_store_dwordx4 v240, v[92:95], s[12:13] nt
	v_mul_f32_e32 v84, s78, v84
	v_mul_f32_e32 v85, s78, v85
	v_mul_f32_e32 v86, s78, v86
	v_mul_f32_e32 v87, s78, v87
	v_mul_f32_e32 v80, s78, v80
	v_mul_f32_e32 v81, s78, v81
	v_mul_f32_e32 v82, s78, v82
	v_mul_f32_e32 v83, s78, v83
	v_cvt_pk_bf16_f32 v84, v84, v85
	v_cvt_pk_bf16_f32 v85, v86, v87
	v_cvt_pk_bf16_f32 v86, v80, v81
	v_cvt_pk_bf16_f32 v87, v82, v83
	global_store_dwordx4 v240, v[84:87], s[12:13] offset:256 nt
	s_add_u32 s12, s12, 0x20800
	s_addc_u32 s13, s13, 0
	v_mul_f32_e32 v76, s78, v76
	v_mul_f32_e32 v77, s78, v77
	v_mul_f32_e32 v78, s78, v78
	v_mul_f32_e32 v79, s78, v79
	v_mul_f32_e32 v72, s78, v72
	v_mul_f32_e32 v73, s78, v73
	v_mul_f32_e32 v74, s78, v74
	v_mul_f32_e32 v75, s78, v75
	v_cvt_pk_bf16_f32 v76, v76, v77
	v_cvt_pk_bf16_f32 v77, v78, v79
	v_cvt_pk_bf16_f32 v78, v72, v73
	v_cvt_pk_bf16_f32 v79, v74, v75
	global_store_dwordx4 v240, v[76:79], s[12:13] nt
	v_mul_f32_e32 v68, s78, v68
	v_mul_f32_e32 v69, s78, v69
	v_mul_f32_e32 v70, s78, v70
	v_mul_f32_e32 v71, s78, v71
	v_mul_f32_e32 v64, s78, v64
	v_mul_f32_e32 v65, s78, v65
	v_mul_f32_e32 v66, s78, v66
	v_mul_f32_e32 v67, s78, v67
	v_cvt_pk_bf16_f32 v68, v68, v69
	v_cvt_pk_bf16_f32 v69, v70, v71
	v_cvt_pk_bf16_f32 v70, v64, v65
	v_cvt_pk_bf16_f32 v71, v66, v67
	global_store_dwordx4 v240, v[68:71], s[12:13] offset:256 nt
	s_add_u32 s12, s12, 0xa2800
	s_addc_u32 s13, s13, 0
	v_mul_f32_e32 v60, s78, v60
	v_mul_f32_e32 v61, s78, v61
	v_mul_f32_e32 v62, s78, v62
	v_mul_f32_e32 v63, s78, v63
	v_mul_f32_e32 v56, s78, v56
	v_mul_f32_e32 v57, s78, v57
	v_mul_f32_e32 v58, s78, v58
	v_mul_f32_e32 v59, s78, v59
	v_cvt_pk_bf16_f32 v60, v60, v61
	v_cvt_pk_bf16_f32 v61, v62, v63
	v_cvt_pk_bf16_f32 v62, v56, v57
	v_cvt_pk_bf16_f32 v63, v58, v59
	global_store_dwordx4 v240, v[60:63], s[12:13] nt
	v_mul_f32_e32 v52, s78, v52
	v_mul_f32_e32 v53, s78, v53
	v_mul_f32_e32 v54, s78, v54
	v_mul_f32_e32 v55, s78, v55
	v_mul_f32_e32 v48, s78, v48
	v_mul_f32_e32 v49, s78, v49
	v_mul_f32_e32 v50, s78, v50
	v_mul_f32_e32 v51, s78, v51
	v_cvt_pk_bf16_f32 v52, v52, v53
	v_cvt_pk_bf16_f32 v53, v54, v55
	v_cvt_pk_bf16_f32 v54, v48, v49
	v_cvt_pk_bf16_f32 v55, v50, v51
	global_store_dwordx4 v240, v[52:55], s[12:13] offset:256 nt
	s_add_u32 s12, s12, 0x20800
	s_addc_u32 s13, s13, 0
	v_mul_f32_e32 v44, s78, v44
	v_mul_f32_e32 v45, s78, v45
	v_mul_f32_e32 v46, s78, v46
	v_mul_f32_e32 v47, s78, v47
	v_mul_f32_e32 v40, s78, v40
	v_mul_f32_e32 v41, s78, v41
	v_mul_f32_e32 v42, s78, v42
	v_mul_f32_e32 v43, s78, v43
	v_cvt_pk_bf16_f32 v44, v44, v45
	v_cvt_pk_bf16_f32 v45, v46, v47
	v_cvt_pk_bf16_f32 v46, v40, v41
	v_cvt_pk_bf16_f32 v47, v42, v43
	global_store_dwordx4 v240, v[44:47], s[12:13] nt
	v_mul_f32_e32 v36, s78, v36
	v_mul_f32_e32 v37, s78, v37
	v_mul_f32_e32 v38, s78, v38
	v_mul_f32_e32 v39, s78, v39
	v_mul_f32_e32 v32, s78, v32
	v_mul_f32_e32 v33, s78, v33
	v_mul_f32_e32 v34, s78, v34
	v_mul_f32_e32 v35, s78, v35
	v_cvt_pk_bf16_f32 v36, v36, v37
	v_cvt_pk_bf16_f32 v37, v38, v39
	v_cvt_pk_bf16_f32 v38, v32, v33
	v_cvt_pk_bf16_f32 v39, v34, v35
	global_store_dwordx4 v240, v[36:39], s[12:13] offset:256 nt
	s_add_u32 s12, s12, 0x20800
	s_addc_u32 s13, s13, 0
	v_mul_f32_e32 v28, s78, v28
	v_mul_f32_e32 v29, s78, v29
	v_mul_f32_e32 v30, s78, v30
	v_mul_f32_e32 v31, s78, v31
	v_mul_f32_e32 v24, s78, v24
	v_mul_f32_e32 v25, s78, v25
	v_mul_f32_e32 v26, s78, v26
	v_mul_f32_e32 v27, s78, v27
	v_cvt_pk_bf16_f32 v28, v28, v29
	v_cvt_pk_bf16_f32 v29, v30, v31
	v_cvt_pk_bf16_f32 v30, v24, v25
	v_cvt_pk_bf16_f32 v31, v26, v27
	global_store_dwordx4 v240, v[28:31], s[12:13] nt
	v_mul_f32_e32 v20, s78, v20
	v_mul_f32_e32 v21, s78, v21
	v_mul_f32_e32 v22, s78, v22
	v_mul_f32_e32 v23, s78, v23
	v_mul_f32_e32 v16, s78, v16
	v_mul_f32_e32 v17, s78, v17
	v_mul_f32_e32 v18, s78, v18
	v_mul_f32_e32 v19, s78, v19
	v_cvt_pk_bf16_f32 v20, v20, v21
	v_cvt_pk_bf16_f32 v21, v22, v23
	v_cvt_pk_bf16_f32 v22, v16, v17
	v_cvt_pk_bf16_f32 v23, v18, v19
	global_store_dwordx4 v240, v[20:23], s[12:13] offset:256 nt
	s_add_u32 s12, s12, 0x20800
	s_addc_u32 s13, s13, 0
	v_mul_f32_e32 v12, s78, v12
	v_mul_f32_e32 v13, s78, v13
	v_mul_f32_e32 v14, s78, v14
	v_mul_f32_e32 v15, s78, v15
	v_mul_f32_e32 v8, s78, v8
	v_mul_f32_e32 v9, s78, v9
	v_mul_f32_e32 v10, s78, v10
	v_mul_f32_e32 v11, s78, v11
	v_cvt_pk_bf16_f32 v12, v12, v13
	v_cvt_pk_bf16_f32 v13, v14, v15
	v_cvt_pk_bf16_f32 v14, v8, v9
	v_cvt_pk_bf16_f32 v15, v10, v11
	global_store_dwordx4 v240, v[12:15], s[12:13] nt
	v_mul_f32_e32 v4, s78, v4
	v_mul_f32_e32 v5, s78, v5
	v_mul_f32_e32 v6, s78, v6
	v_mul_f32_e32 v7, s78, v7
	v_mul_f32_e32 v0, s78, v0
	v_mul_f32_e32 v1, s78, v1
	v_mul_f32_e32 v2, s78, v2
	v_mul_f32_e32 v3, s78, v3
	v_cvt_pk_bf16_f32 v4, v4, v5
	v_cvt_pk_bf16_f32 v5, v6, v7
	v_cvt_pk_bf16_f32 v6, v0, v1
	v_cvt_pk_bf16_f32 v7, v2, v3
	global_store_dwordx4 v240, v[4:7], s[12:13] offset:256 nt
	s_branch .Lfe_join
.Lfe_gf:
	s_mul_i32 s9, s10, 20
	s_add_i32 s9, s9, s8
	s_add_i32 s9, s9, -16
	s_lshl_b32 s9, s9, 17
	s_lshl_b32 s11, s84, 1
	s_add_i32 s9, s9, s11
	s_add_u32 s12, s37, s9
	s_addc_u32 s13, s4, 0
	v_lshlrev_b32_e32 v240, 8, v177
	v_lshl_add_u32 v240, v176, 4, v240
	s_cmp_gt_i32 s33, 9
	s_cbranch_scc1 .Lfe_gf_sig
	v_mul_f32_e32 v248, 0xbfb8aa3b, v124
	v_mul_f32_e32 v249, 0xbfb8aa3b, v125
	v_mul_f32_e32 v250, 0xbfb8aa3b, v126
	v_mul_f32_e32 v251, 0xbfb8aa3b, v127
	v_mul_f32_e32 v252, 0xbfb8aa3b, v120
	v_mul_f32_e32 v253, 0xbfb8aa3b, v121
	v_mul_f32_e32 v254, 0xbfb8aa3b, v122
	v_mul_f32_e32 v255, 0xbfb8aa3b, v123
	v_exp_f32_e32 v248, v248
	v_exp_f32_e32 v249, v249
	v_exp_f32_e32 v250, v250
	v_exp_f32_e32 v251, v251
	v_exp_f32_e32 v252, v252
	v_exp_f32_e32 v253, v253
	v_exp_f32_e32 v254, v254
	v_exp_f32_e32 v255, v255
	v_add_f32_e32 v248, 1.0, v248
	v_add_f32_e32 v249, 1.0, v249
	v_add_f32_e32 v250, 1.0, v250
	v_add_f32_e32 v251, 1.0, v251
	v_add_f32_e32 v252, 1.0, v252
	v_add_f32_e32 v253, 1.0, v253
	v_add_f32_e32 v254, 1.0, v254
	v_add_f32_e32 v255, 1.0, v255
	v_rcp_f32_e32 v248, v248
	v_rcp_f32_e32 v249, v249
	v_rcp_f32_e32 v250, v250
	v_rcp_f32_e32 v251, v251
	v_rcp_f32_e32 v252, v252
	v_rcp_f32_e32 v253, v253
	v_rcp_f32_e32 v254, v254
	v_rcp_f32_e32 v255, v255
	v_mul_f32_e32 v124, v124, v248
	v_mul_f32_e32 v125, v125, v249
	v_mul_f32_e32 v126, v126, v250
	v_mul_f32_e32 v127, v127, v251
	v_mul_f32_e32 v120, v120, v252
	v_mul_f32_e32 v121, v121, v253
	v_mul_f32_e32 v122, v122, v254
	v_mul_f32_e32 v123, v123, v255
	v_cvt_pk_bf16_f32 v124, v124, v125
	v_cvt_pk_bf16_f32 v125, v126, v127
	v_cvt_pk_bf16_f32 v126, v120, v121
	v_cvt_pk_bf16_f32 v127, v122, v123
	global_store_dwordx4 v240, v[124:127], s[12:13] nt
	v_mul_f32_e32 v248, 0xbfb8aa3b, v116
	v_mul_f32_e32 v249, 0xbfb8aa3b, v117
	v_mul_f32_e32 v250, 0xbfb8aa3b, v118
	v_mul_f32_e32 v251, 0xbfb8aa3b, v119
	v_mul_f32_e32 v252, 0xbfb8aa3b, v112
	v_mul_f32_e32 v253, 0xbfb8aa3b, v113
	v_mul_f32_e32 v254, 0xbfb8aa3b, v114
	v_mul_f32_e32 v255, 0xbfb8aa3b, v115
	v_exp_f32_e32 v248, v248
	v_exp_f32_e32 v249, v249
	v_exp_f32_e32 v250, v250
	v_exp_f32_e32 v251, v251
	v_exp_f32_e32 v252, v252
	v_exp_f32_e32 v253, v253
	v_exp_f32_e32 v254, v254
	v_exp_f32_e32 v255, v255
	v_add_f32_e32 v248, 1.0, v248
	v_add_f32_e32 v249, 1.0, v249
	v_add_f32_e32 v250, 1.0, v250
	v_add_f32_e32 v251, 1.0, v251
	v_add_f32_e32 v252, 1.0, v252
	v_add_f32_e32 v253, 1.0, v253
	v_add_f32_e32 v254, 1.0, v254
	v_add_f32_e32 v255, 1.0, v255
	v_rcp_f32_e32 v248, v248
	v_rcp_f32_e32 v249, v249
	v_rcp_f32_e32 v250, v250
	v_rcp_f32_e32 v251, v251
	v_rcp_f32_e32 v252, v252
	v_rcp_f32_e32 v253, v253
	v_rcp_f32_e32 v254, v254
	v_rcp_f32_e32 v255, v255
	v_mul_f32_e32 v116, v116, v248
	v_mul_f32_e32 v117, v117, v249
	v_mul_f32_e32 v118, v118, v250
	v_mul_f32_e32 v119, v119, v251
	v_mul_f32_e32 v112, v112, v252
	v_mul_f32_e32 v113, v113, v253
	v_mul_f32_e32 v114, v114, v254
	v_mul_f32_e32 v115, v115, v255
	v_cvt_pk_bf16_f32 v116, v116, v117
	v_cvt_pk_bf16_f32 v117, v118, v119
	v_cvt_pk_bf16_f32 v118, v112, v113
	v_cvt_pk_bf16_f32 v119, v114, v115
	global_store_dwordx4 v240, v[116:119], s[12:13] offset:1024 nt
	s_add_u32 s12, s12, 0x800
	s_addc_u32 s13, s13, 0
	v_mul_f32_e32 v248, 0xbfb8aa3b, v108
	v_mul_f32_e32 v249, 0xbfb8aa3b, v109
	v_mul_f32_e32 v250, 0xbfb8aa3b, v110
	v_mul_f32_e32 v251, 0xbfb8aa3b, v111
	v_mul_f32_e32 v252, 0xbfb8aa3b, v104
	v_mul_f32_e32 v253, 0xbfb8aa3b, v105
	v_mul_f32_e32 v254, 0xbfb8aa3b, v106
	v_mul_f32_e32 v255, 0xbfb8aa3b, v107
	v_exp_f32_e32 v248, v248
	v_exp_f32_e32 v249, v249
	v_exp_f32_e32 v250, v250
	v_exp_f32_e32 v251, v251
	v_exp_f32_e32 v252, v252
	v_exp_f32_e32 v253, v253
	v_exp_f32_e32 v254, v254
	v_exp_f32_e32 v255, v255
	v_add_f32_e32 v248, 1.0, v248
	v_add_f32_e32 v249, 1.0, v249
	v_add_f32_e32 v250, 1.0, v250
	v_add_f32_e32 v251, 1.0, v251
	v_add_f32_e32 v252, 1.0, v252
	v_add_f32_e32 v253, 1.0, v253
	v_add_f32_e32 v254, 1.0, v254
	v_add_f32_e32 v255, 1.0, v255
	v_rcp_f32_e32 v248, v248
	v_rcp_f32_e32 v249, v249
	v_rcp_f32_e32 v250, v250
	v_rcp_f32_e32 v251, v251
	v_rcp_f32_e32 v252, v252
	v_rcp_f32_e32 v253, v253
	v_rcp_f32_e32 v254, v254
	v_rcp_f32_e32 v255, v255
	v_mul_f32_e32 v108, v108, v248
	v_mul_f32_e32 v109, v109, v249
	v_mul_f32_e32 v110, v110, v250
	v_mul_f32_e32 v111, v111, v251
	v_mul_f32_e32 v104, v104, v252
	v_mul_f32_e32 v105, v105, v253
	v_mul_f32_e32 v106, v106, v254
	v_mul_f32_e32 v107, v107, v255
	v_cvt_pk_bf16_f32 v108, v108, v109
	v_cvt_pk_bf16_f32 v109, v110, v111
	v_cvt_pk_bf16_f32 v110, v104, v105
	v_cvt_pk_bf16_f32 v111, v106, v107
	global_store_dwordx4 v240, v[108:111], s[12:13] nt
	v_mul_f32_e32 v248, 0xbfb8aa3b, v100
	v_mul_f32_e32 v249, 0xbfb8aa3b, v101
	v_mul_f32_e32 v250, 0xbfb8aa3b, v102
	v_mul_f32_e32 v251, 0xbfb8aa3b, v103
	v_mul_f32_e32 v252, 0xbfb8aa3b, v96
	v_mul_f32_e32 v253, 0xbfb8aa3b, v97
	v_mul_f32_e32 v254, 0xbfb8aa3b, v98
	v_mul_f32_e32 v255, 0xbfb8aa3b, v99
	v_exp_f32_e32 v248, v248
	v_exp_f32_e32 v249, v249
	v_exp_f32_e32 v250, v250
	v_exp_f32_e32 v251, v251
	v_exp_f32_e32 v252, v252
	v_exp_f32_e32 v253, v253
	v_exp_f32_e32 v254, v254
	v_exp_f32_e32 v255, v255
	v_add_f32_e32 v248, 1.0, v248
	v_add_f32_e32 v249, 1.0, v249
	v_add_f32_e32 v250, 1.0, v250
	v_add_f32_e32 v251, 1.0, v251
	v_add_f32_e32 v252, 1.0, v252
	v_add_f32_e32 v253, 1.0, v253
	v_add_f32_e32 v254, 1.0, v254
	v_add_f32_e32 v255, 1.0, v255
	v_rcp_f32_e32 v248, v248
	v_rcp_f32_e32 v249, v249
	v_rcp_f32_e32 v250, v250
	v_rcp_f32_e32 v251, v251
	v_rcp_f32_e32 v252, v252
	v_rcp_f32_e32 v253, v253
	v_rcp_f32_e32 v254, v254
	v_rcp_f32_e32 v255, v255
	v_mul_f32_e32 v100, v100, v248
	v_mul_f32_e32 v101, v101, v249
	v_mul_f32_e32 v102, v102, v250
	v_mul_f32_e32 v103, v103, v251
	v_mul_f32_e32 v96, v96, v252
	v_mul_f32_e32 v97, v97, v253
	v_mul_f32_e32 v98, v98, v254
	v_mul_f32_e32 v99, v99, v255
	v_cvt_pk_bf16_f32 v100, v100, v101
	v_cvt_pk_bf16_f32 v101, v102, v103
	v_cvt_pk_bf16_f32 v102, v96, v97
	v_cvt_pk_bf16_f32 v103, v98, v99
	global_store_dwordx4 v240, v[100:103], s[12:13] offset:1024 nt
	s_add_u32 s12, s12, 0x800
	s_addc_u32 s13, s13, 0
	v_mul_f32_e32 v248, 0xbfb8aa3b, v92
	v_mul_f32_e32 v249, 0xbfb8aa3b, v93
	v_mul_f32_e32 v250, 0xbfb8aa3b, v94
	v_mul_f32_e32 v251, 0xbfb8aa3b, v95
	v_mul_f32_e32 v252, 0xbfb8aa3b, v88
	v_mul_f32_e32 v253, 0xbfb8aa3b, v89
	v_mul_f32_e32 v254, 0xbfb8aa3b, v90
	v_mul_f32_e32 v255, 0xbfb8aa3b, v91
	v_exp_f32_e32 v248, v248
	v_exp_f32_e32 v249, v249
	v_exp_f32_e32 v250, v250
	v_exp_f32_e32 v251, v251
	v_exp_f32_e32 v252, v252
	v_exp_f32_e32 v253, v253
	v_exp_f32_e32 v254, v254
	v_exp_f32_e32 v255, v255
	v_add_f32_e32 v248, 1.0, v248
	v_add_f32_e32 v249, 1.0, v249
	v_add_f32_e32 v250, 1.0, v250
	v_add_f32_e32 v251, 1.0, v251
	v_add_f32_e32 v252, 1.0, v252
	v_add_f32_e32 v253, 1.0, v253
	v_add_f32_e32 v254, 1.0, v254
	v_add_f32_e32 v255, 1.0, v255
	v_rcp_f32_e32 v248, v248
	v_rcp_f32_e32 v249, v249
	v_rcp_f32_e32 v250, v250
	v_rcp_f32_e32 v251, v251
	v_rcp_f32_e32 v252, v252
	v_rcp_f32_e32 v253, v253
	v_rcp_f32_e32 v254, v254
	v_rcp_f32_e32 v255, v255
	v_mul_f32_e32 v92, v92, v248
	v_mul_f32_e32 v93, v93, v249
	v_mul_f32_e32 v94, v94, v250
	v_mul_f32_e32 v95, v95, v251
	v_mul_f32_e32 v88, v88, v252
	v_mul_f32_e32 v89, v89, v253
	v_mul_f32_e32 v90, v90, v254
	v_mul_f32_e32 v91, v91, v255
	v_cvt_pk_bf16_f32 v92, v92, v93
	v_cvt_pk_bf16_f32 v93, v94, v95
	v_cvt_pk_bf16_f32 v94, v88, v89
	v_cvt_pk_bf16_f32 v95, v90, v91
	global_store_dwordx4 v240, v[92:95], s[12:13] nt
	v_mul_f32_e32 v248, 0xbfb8aa3b, v84
	v_mul_f32_e32 v249, 0xbfb8aa3b, v85
	v_mul_f32_e32 v250, 0xbfb8aa3b, v86
	v_mul_f32_e32 v251, 0xbfb8aa3b, v87
	v_mul_f32_e32 v252, 0xbfb8aa3b, v80
	v_mul_f32_e32 v253, 0xbfb8aa3b, v81
	v_mul_f32_e32 v254, 0xbfb8aa3b, v82
	v_mul_f32_e32 v255, 0xbfb8aa3b, v83
	v_exp_f32_e32 v248, v248
	v_exp_f32_e32 v249, v249
	v_exp_f32_e32 v250, v250
	v_exp_f32_e32 v251, v251
	v_exp_f32_e32 v252, v252
	v_exp_f32_e32 v253, v253
	v_exp_f32_e32 v254, v254
	v_exp_f32_e32 v255, v255
	v_add_f32_e32 v248, 1.0, v248
	v_add_f32_e32 v249, 1.0, v249
	v_add_f32_e32 v250, 1.0, v250
	v_add_f32_e32 v251, 1.0, v251
	v_add_f32_e32 v252, 1.0, v252
	v_add_f32_e32 v253, 1.0, v253
	v_add_f32_e32 v254, 1.0, v254
	v_add_f32_e32 v255, 1.0, v255
	v_rcp_f32_e32 v248, v248
	v_rcp_f32_e32 v249, v249
	v_rcp_f32_e32 v250, v250
	v_rcp_f32_e32 v251, v251
	v_rcp_f32_e32 v252, v252
	v_rcp_f32_e32 v253, v253
	v_rcp_f32_e32 v254, v254
	v_rcp_f32_e32 v255, v255
	v_mul_f32_e32 v84, v84, v248
	v_mul_f32_e32 v85, v85, v249
	v_mul_f32_e32 v86, v86, v250
	v_mul_f32_e32 v87, v87, v251
	v_mul_f32_e32 v80, v80, v252
	v_mul_f32_e32 v81, v81, v253
	v_mul_f32_e32 v82, v82, v254
	v_mul_f32_e32 v83, v83, v255
	v_cvt_pk_bf16_f32 v84, v84, v85
	v_cvt_pk_bf16_f32 v85, v86, v87
	v_cvt_pk_bf16_f32 v86, v80, v81
	v_cvt_pk_bf16_f32 v87, v82, v83
	global_store_dwordx4 v240, v[84:87], s[12:13] offset:1024 nt
	s_add_u32 s12, s12, 0x800
	s_addc_u32 s13, s13, 0
	v_mul_f32_e32 v248, 0xbfb8aa3b, v76
	v_mul_f32_e32 v249, 0xbfb8aa3b, v77
	v_mul_f32_e32 v250, 0xbfb8aa3b, v78
	v_mul_f32_e32 v251, 0xbfb8aa3b, v79
	v_mul_f32_e32 v252, 0xbfb8aa3b, v72
	v_mul_f32_e32 v253, 0xbfb8aa3b, v73
	v_mul_f32_e32 v254, 0xbfb8aa3b, v74
	v_mul_f32_e32 v255, 0xbfb8aa3b, v75
	v_exp_f32_e32 v248, v248
	v_exp_f32_e32 v249, v249
	v_exp_f32_e32 v250, v250
	v_exp_f32_e32 v251, v251
	v_exp_f32_e32 v252, v252
	v_exp_f32_e32 v253, v253
	v_exp_f32_e32 v254, v254
	v_exp_f32_e32 v255, v255
	v_add_f32_e32 v248, 1.0, v248
	v_add_f32_e32 v249, 1.0, v249
	v_add_f32_e32 v250, 1.0, v250
	v_add_f32_e32 v251, 1.0, v251
	v_add_f32_e32 v252, 1.0, v252
	v_add_f32_e32 v253, 1.0, v253
	v_add_f32_e32 v254, 1.0, v254
	v_add_f32_e32 v255, 1.0, v255
	v_rcp_f32_e32 v248, v248
	v_rcp_f32_e32 v249, v249
	v_rcp_f32_e32 v250, v250
	v_rcp_f32_e32 v251, v251
	v_rcp_f32_e32 v252, v252
	v_rcp_f32_e32 v253, v253
	v_rcp_f32_e32 v254, v254
	v_rcp_f32_e32 v255, v255
	v_mul_f32_e32 v76, v76, v248
	v_mul_f32_e32 v77, v77, v249
	v_mul_f32_e32 v78, v78, v250
	v_mul_f32_e32 v79, v79, v251
	v_mul_f32_e32 v72, v72, v252
	v_mul_f32_e32 v73, v73, v253
	v_mul_f32_e32 v74, v74, v254
	v_mul_f32_e32 v75, v75, v255
	v_cvt_pk_bf16_f32 v76, v76, v77
	v_cvt_pk_bf16_f32 v77, v78, v79
	v_cvt_pk_bf16_f32 v78, v72, v73
	v_cvt_pk_bf16_f32 v79, v74, v75
	global_store_dwordx4 v240, v[76:79], s[12:13] nt
	v_mul_f32_e32 v248, 0xbfb8aa3b, v68
	v_mul_f32_e32 v249, 0xbfb8aa3b, v69
	v_mul_f32_e32 v250, 0xbfb8aa3b, v70
	v_mul_f32_e32 v251, 0xbfb8aa3b, v71
	v_mul_f32_e32 v252, 0xbfb8aa3b, v64
	v_mul_f32_e32 v253, 0xbfb8aa3b, v65
	v_mul_f32_e32 v254, 0xbfb8aa3b, v66
	v_mul_f32_e32 v255, 0xbfb8aa3b, v67
	v_exp_f32_e32 v248, v248
	v_exp_f32_e32 v249, v249
	v_exp_f32_e32 v250, v250
	v_exp_f32_e32 v251, v251
	v_exp_f32_e32 v252, v252
	v_exp_f32_e32 v253, v253
	v_exp_f32_e32 v254, v254
	v_exp_f32_e32 v255, v255
	v_add_f32_e32 v248, 1.0, v248
	v_add_f32_e32 v249, 1.0, v249
	v_add_f32_e32 v250, 1.0, v250
	v_add_f32_e32 v251, 1.0, v251
	v_add_f32_e32 v252, 1.0, v252
	v_add_f32_e32 v253, 1.0, v253
	v_add_f32_e32 v254, 1.0, v254
	v_add_f32_e32 v255, 1.0, v255
	v_rcp_f32_e32 v248, v248
	v_rcp_f32_e32 v249, v249
	v_rcp_f32_e32 v250, v250
	v_rcp_f32_e32 v251, v251
	v_rcp_f32_e32 v252, v252
	v_rcp_f32_e32 v253, v253
	v_rcp_f32_e32 v254, v254
	v_rcp_f32_e32 v255, v255
	v_mul_f32_e32 v68, v68, v248
	v_mul_f32_e32 v69, v69, v249
	v_mul_f32_e32 v70, v70, v250
	v_mul_f32_e32 v71, v71, v251
	v_mul_f32_e32 v64, v64, v252
	v_mul_f32_e32 v65, v65, v253
	v_mul_f32_e32 v66, v66, v254
	v_mul_f32_e32 v67, v67, v255
	v_cvt_pk_bf16_f32 v68, v68, v69
	v_cvt_pk_bf16_f32 v69, v70, v71
	v_cvt_pk_bf16_f32 v70, v64, v65
	v_cvt_pk_bf16_f32 v71, v66, v67
	global_store_dwordx4 v240, v[68:71], s[12:13] offset:1024 nt
	s_add_u32 s12, s12, 0x800
	s_addc_u32 s13, s13, 0
	v_mul_f32_e32 v248, 0xbfb8aa3b, v60
	v_mul_f32_e32 v249, 0xbfb8aa3b, v61
	v_mul_f32_e32 v250, 0xbfb8aa3b, v62
	v_mul_f32_e32 v251, 0xbfb8aa3b, v63
	v_mul_f32_e32 v252, 0xbfb8aa3b, v56
	v_mul_f32_e32 v253, 0xbfb8aa3b, v57
	v_mul_f32_e32 v254, 0xbfb8aa3b, v58
	v_mul_f32_e32 v255, 0xbfb8aa3b, v59
	v_exp_f32_e32 v248, v248
	v_exp_f32_e32 v249, v249
	v_exp_f32_e32 v250, v250
	v_exp_f32_e32 v251, v251
	v_exp_f32_e32 v252, v252
	v_exp_f32_e32 v253, v253
	v_exp_f32_e32 v254, v254
	v_exp_f32_e32 v255, v255
	v_add_f32_e32 v248, 1.0, v248
	v_add_f32_e32 v249, 1.0, v249
	v_add_f32_e32 v250, 1.0, v250
	v_add_f32_e32 v251, 1.0, v251
	v_add_f32_e32 v252, 1.0, v252
	v_add_f32_e32 v253, 1.0, v253
	v_add_f32_e32 v254, 1.0, v254
	v_add_f32_e32 v255, 1.0, v255
	v_rcp_f32_e32 v248, v248
	v_rcp_f32_e32 v249, v249
	v_rcp_f32_e32 v250, v250
	v_rcp_f32_e32 v251, v251
	v_rcp_f32_e32 v252, v252
	v_rcp_f32_e32 v253, v253
	v_rcp_f32_e32 v254, v254
	v_rcp_f32_e32 v255, v255
	v_mul_f32_e32 v60, v60, v248
	v_mul_f32_e32 v61, v61, v249
	v_mul_f32_e32 v62, v62, v250
	v_mul_f32_e32 v63, v63, v251
	v_mul_f32_e32 v56, v56, v252
	v_mul_f32_e32 v57, v57, v253
	v_mul_f32_e32 v58, v58, v254
	v_mul_f32_e32 v59, v59, v255
	v_cvt_pk_bf16_f32 v60, v60, v61
	v_cvt_pk_bf16_f32 v61, v62, v63
	v_cvt_pk_bf16_f32 v62, v56, v57
	v_cvt_pk_bf16_f32 v63, v58, v59
	global_store_dwordx4 v240, v[60:63], s[12:13] nt
	v_mul_f32_e32 v248, 0xbfb8aa3b, v52
	v_mul_f32_e32 v249, 0xbfb8aa3b, v53
	v_mul_f32_e32 v250, 0xbfb8aa3b, v54
	v_mul_f32_e32 v251, 0xbfb8aa3b, v55
	v_mul_f32_e32 v252, 0xbfb8aa3b, v48
	v_mul_f32_e32 v253, 0xbfb8aa3b, v49
	v_mul_f32_e32 v254, 0xbfb8aa3b, v50
	v_mul_f32_e32 v255, 0xbfb8aa3b, v51
	v_exp_f32_e32 v248, v248
	v_exp_f32_e32 v249, v249
	v_exp_f32_e32 v250, v250
	v_exp_f32_e32 v251, v251
	v_exp_f32_e32 v252, v252
	v_exp_f32_e32 v253, v253
	v_exp_f32_e32 v254, v254
	v_exp_f32_e32 v255, v255
	v_add_f32_e32 v248, 1.0, v248
	v_add_f32_e32 v249, 1.0, v249
	v_add_f32_e32 v250, 1.0, v250
	v_add_f32_e32 v251, 1.0, v251
	v_add_f32_e32 v252, 1.0, v252
	v_add_f32_e32 v253, 1.0, v253
	v_add_f32_e32 v254, 1.0, v254
	v_add_f32_e32 v255, 1.0, v255
	v_rcp_f32_e32 v248, v248
	v_rcp_f32_e32 v249, v249
	v_rcp_f32_e32 v250, v250
	v_rcp_f32_e32 v251, v251
	v_rcp_f32_e32 v252, v252
	v_rcp_f32_e32 v253, v253
	v_rcp_f32_e32 v254, v254
	v_rcp_f32_e32 v255, v255
	v_mul_f32_e32 v52, v52, v248
	v_mul_f32_e32 v53, v53, v249
	v_mul_f32_e32 v54, v54, v250
	v_mul_f32_e32 v55, v55, v251
	v_mul_f32_e32 v48, v48, v252
	v_mul_f32_e32 v49, v49, v253
	v_mul_f32_e32 v50, v50, v254
	v_mul_f32_e32 v51, v51, v255
	v_cvt_pk_bf16_f32 v52, v52, v53
	v_cvt_pk_bf16_f32 v53, v54, v55
	v_cvt_pk_bf16_f32 v54, v48, v49
	v_cvt_pk_bf16_f32 v55, v50, v51
	global_store_dwordx4 v240, v[52:55], s[12:13] offset:1024 nt
	s_add_u32 s12, s12, 0x800
	s_addc_u32 s13, s13, 0
	v_mul_f32_e32 v248, 0xbfb8aa3b, v44
	v_mul_f32_e32 v249, 0xbfb8aa3b, v45
	v_mul_f32_e32 v250, 0xbfb8aa3b, v46
	v_mul_f32_e32 v251, 0xbfb8aa3b, v47
	v_mul_f32_e32 v252, 0xbfb8aa3b, v40
	v_mul_f32_e32 v253, 0xbfb8aa3b, v41
	v_mul_f32_e32 v254, 0xbfb8aa3b, v42
	v_mul_f32_e32 v255, 0xbfb8aa3b, v43
	v_exp_f32_e32 v248, v248
	v_exp_f32_e32 v249, v249
	v_exp_f32_e32 v250, v250
	v_exp_f32_e32 v251, v251
	v_exp_f32_e32 v252, v252
	v_exp_f32_e32 v253, v253
	v_exp_f32_e32 v254, v254
	v_exp_f32_e32 v255, v255
	v_add_f32_e32 v248, 1.0, v248
	v_add_f32_e32 v249, 1.0, v249
	v_add_f32_e32 v250, 1.0, v250
	v_add_f32_e32 v251, 1.0, v251
	v_add_f32_e32 v252, 1.0, v252
	v_add_f32_e32 v253, 1.0, v253
	v_add_f32_e32 v254, 1.0, v254
	v_add_f32_e32 v255, 1.0, v255
	v_rcp_f32_e32 v248, v248
	v_rcp_f32_e32 v249, v249
	v_rcp_f32_e32 v250, v250
	v_rcp_f32_e32 v251, v251
	v_rcp_f32_e32 v252, v252
	v_rcp_f32_e32 v253, v253
	v_rcp_f32_e32 v254, v254
	v_rcp_f32_e32 v255, v255
	v_mul_f32_e32 v44, v44, v248
	v_mul_f32_e32 v45, v45, v249
	v_mul_f32_e32 v46, v46, v250
	v_mul_f32_e32 v47, v47, v251
	v_mul_f32_e32 v40, v40, v252
	v_mul_f32_e32 v41, v41, v253
	v_mul_f32_e32 v42, v42, v254
	v_mul_f32_e32 v43, v43, v255
	v_cvt_pk_bf16_f32 v44, v44, v45
	v_cvt_pk_bf16_f32 v45, v46, v47
	v_cvt_pk_bf16_f32 v46, v40, v41
	v_cvt_pk_bf16_f32 v47, v42, v43
	global_store_dwordx4 v240, v[44:47], s[12:13] nt
	v_mul_f32_e32 v248, 0xbfb8aa3b, v36
	v_mul_f32_e32 v249, 0xbfb8aa3b, v37
	v_mul_f32_e32 v250, 0xbfb8aa3b, v38
	v_mul_f32_e32 v251, 0xbfb8aa3b, v39
	v_mul_f32_e32 v252, 0xbfb8aa3b, v32
	v_mul_f32_e32 v253, 0xbfb8aa3b, v33
	v_mul_f32_e32 v254, 0xbfb8aa3b, v34
	v_mul_f32_e32 v255, 0xbfb8aa3b, v35
	v_exp_f32_e32 v248, v248
	v_exp_f32_e32 v249, v249
	v_exp_f32_e32 v250, v250
	v_exp_f32_e32 v251, v251
	v_exp_f32_e32 v252, v252
	v_exp_f32_e32 v253, v253
	v_exp_f32_e32 v254, v254
	v_exp_f32_e32 v255, v255
	v_add_f32_e32 v248, 1.0, v248
	v_add_f32_e32 v249, 1.0, v249
	v_add_f32_e32 v250, 1.0, v250
	v_add_f32_e32 v251, 1.0, v251
	v_add_f32_e32 v252, 1.0, v252
	v_add_f32_e32 v253, 1.0, v253
	v_add_f32_e32 v254, 1.0, v254
	v_add_f32_e32 v255, 1.0, v255
	v_rcp_f32_e32 v248, v248
	v_rcp_f32_e32 v249, v249
	v_rcp_f32_e32 v250, v250
	v_rcp_f32_e32 v251, v251
	v_rcp_f32_e32 v252, v252
	v_rcp_f32_e32 v253, v253
	v_rcp_f32_e32 v254, v254
	v_rcp_f32_e32 v255, v255
	v_mul_f32_e32 v36, v36, v248
	v_mul_f32_e32 v37, v37, v249
	v_mul_f32_e32 v38, v38, v250
	v_mul_f32_e32 v39, v39, v251
	v_mul_f32_e32 v32, v32, v252
	v_mul_f32_e32 v33, v33, v253
	v_mul_f32_e32 v34, v34, v254
	v_mul_f32_e32 v35, v35, v255
	v_cvt_pk_bf16_f32 v36, v36, v37
	v_cvt_pk_bf16_f32 v37, v38, v39
	v_cvt_pk_bf16_f32 v38, v32, v33
	v_cvt_pk_bf16_f32 v39, v34, v35
	global_store_dwordx4 v240, v[36:39], s[12:13] offset:1024 nt
	s_add_u32 s12, s12, 0x800
	s_addc_u32 s13, s13, 0
	v_mul_f32_e32 v248, 0xbfb8aa3b, v28
	v_mul_f32_e32 v249, 0xbfb8aa3b, v29
	v_mul_f32_e32 v250, 0xbfb8aa3b, v30
	v_mul_f32_e32 v251, 0xbfb8aa3b, v31
	v_mul_f32_e32 v252, 0xbfb8aa3b, v24
	v_mul_f32_e32 v253, 0xbfb8aa3b, v25
	v_mul_f32_e32 v254, 0xbfb8aa3b, v26
	v_mul_f32_e32 v255, 0xbfb8aa3b, v27
	v_exp_f32_e32 v248, v248
	v_exp_f32_e32 v249, v249
	v_exp_f32_e32 v250, v250
	v_exp_f32_e32 v251, v251
	v_exp_f32_e32 v252, v252
	v_exp_f32_e32 v253, v253
	v_exp_f32_e32 v254, v254
	v_exp_f32_e32 v255, v255
	v_add_f32_e32 v248, 1.0, v248
	v_add_f32_e32 v249, 1.0, v249
	v_add_f32_e32 v250, 1.0, v250
	v_add_f32_e32 v251, 1.0, v251
	v_add_f32_e32 v252, 1.0, v252
	v_add_f32_e32 v253, 1.0, v253
	v_add_f32_e32 v254, 1.0, v254
	v_add_f32_e32 v255, 1.0, v255
	v_rcp_f32_e32 v248, v248
	v_rcp_f32_e32 v249, v249
	v_rcp_f32_e32 v250, v250
	v_rcp_f32_e32 v251, v251
	v_rcp_f32_e32 v252, v252
	v_rcp_f32_e32 v253, v253
	v_rcp_f32_e32 v254, v254
	v_rcp_f32_e32 v255, v255
	v_mul_f32_e32 v28, v28, v248
	v_mul_f32_e32 v29, v29, v249
	v_mul_f32_e32 v30, v30, v250
	v_mul_f32_e32 v31, v31, v251
	v_mul_f32_e32 v24, v24, v252
	v_mul_f32_e32 v25, v25, v253
	v_mul_f32_e32 v26, v26, v254
	v_mul_f32_e32 v27, v27, v255
	v_cvt_pk_bf16_f32 v28, v28, v29
	v_cvt_pk_bf16_f32 v29, v30, v31
	v_cvt_pk_bf16_f32 v30, v24, v25
	v_cvt_pk_bf16_f32 v31, v26, v27
	global_store_dwordx4 v240, v[28:31], s[12:13] nt
	v_mul_f32_e32 v248, 0xbfb8aa3b, v20
	v_mul_f32_e32 v249, 0xbfb8aa3b, v21
	v_mul_f32_e32 v250, 0xbfb8aa3b, v22
	v_mul_f32_e32 v251, 0xbfb8aa3b, v23
	v_mul_f32_e32 v252, 0xbfb8aa3b, v16
	v_mul_f32_e32 v253, 0xbfb8aa3b, v17
	v_mul_f32_e32 v254, 0xbfb8aa3b, v18
	v_mul_f32_e32 v255, 0xbfb8aa3b, v19
	v_exp_f32_e32 v248, v248
	v_exp_f32_e32 v249, v249
	v_exp_f32_e32 v250, v250
	v_exp_f32_e32 v251, v251
	v_exp_f32_e32 v252, v252
	v_exp_f32_e32 v253, v253
	v_exp_f32_e32 v254, v254
	v_exp_f32_e32 v255, v255
	v_add_f32_e32 v248, 1.0, v248
	v_add_f32_e32 v249, 1.0, v249
	v_add_f32_e32 v250, 1.0, v250
	v_add_f32_e32 v251, 1.0, v251
	v_add_f32_e32 v252, 1.0, v252
	v_add_f32_e32 v253, 1.0, v253
	v_add_f32_e32 v254, 1.0, v254
	v_add_f32_e32 v255, 1.0, v255
	v_rcp_f32_e32 v248, v248
	v_rcp_f32_e32 v249, v249
	v_rcp_f32_e32 v250, v250
	v_rcp_f32_e32 v251, v251
	v_rcp_f32_e32 v252, v252
	v_rcp_f32_e32 v253, v253
	v_rcp_f32_e32 v254, v254
	v_rcp_f32_e32 v255, v255
	v_mul_f32_e32 v20, v20, v248
	v_mul_f32_e32 v21, v21, v249
	v_mul_f32_e32 v22, v22, v250
	v_mul_f32_e32 v23, v23, v251
	v_mul_f32_e32 v16, v16, v252
	v_mul_f32_e32 v17, v17, v253
	v_mul_f32_e32 v18, v18, v254
	v_mul_f32_e32 v19, v19, v255
	v_cvt_pk_bf16_f32 v20, v20, v21
	v_cvt_pk_bf16_f32 v21, v22, v23
	v_cvt_pk_bf16_f32 v22, v16, v17
	v_cvt_pk_bf16_f32 v23, v18, v19
	global_store_dwordx4 v240, v[20:23], s[12:13] offset:1024 nt
	s_add_u32 s12, s12, 0x800
	s_addc_u32 s13, s13, 0
	v_mul_f32_e32 v248, 0xbfb8aa3b, v12
	v_mul_f32_e32 v249, 0xbfb8aa3b, v13
	v_mul_f32_e32 v250, 0xbfb8aa3b, v14
	v_mul_f32_e32 v251, 0xbfb8aa3b, v15
	v_mul_f32_e32 v252, 0xbfb8aa3b, v8
	v_mul_f32_e32 v253, 0xbfb8aa3b, v9
	v_mul_f32_e32 v254, 0xbfb8aa3b, v10
	v_mul_f32_e32 v255, 0xbfb8aa3b, v11
	v_exp_f32_e32 v248, v248
	v_exp_f32_e32 v249, v249
	v_exp_f32_e32 v250, v250
	v_exp_f32_e32 v251, v251
	v_exp_f32_e32 v252, v252
	v_exp_f32_e32 v253, v253
	v_exp_f32_e32 v254, v254
	v_exp_f32_e32 v255, v255
	v_add_f32_e32 v248, 1.0, v248
	v_add_f32_e32 v249, 1.0, v249
	v_add_f32_e32 v250, 1.0, v250
	v_add_f32_e32 v251, 1.0, v251
	v_add_f32_e32 v252, 1.0, v252
	v_add_f32_e32 v253, 1.0, v253
	v_add_f32_e32 v254, 1.0, v254
	v_add_f32_e32 v255, 1.0, v255
	v_rcp_f32_e32 v248, v248
	v_rcp_f32_e32 v249, v249
	v_rcp_f32_e32 v250, v250
	v_rcp_f32_e32 v251, v251
	v_rcp_f32_e32 v252, v252
	v_rcp_f32_e32 v253, v253
	v_rcp_f32_e32 v254, v254
	v_rcp_f32_e32 v255, v255
	v_mul_f32_e32 v12, v12, v248
	v_mul_f32_e32 v13, v13, v249
	v_mul_f32_e32 v14, v14, v250
	v_mul_f32_e32 v15, v15, v251
	v_mul_f32_e32 v8, v8, v252
	v_mul_f32_e32 v9, v9, v253
	v_mul_f32_e32 v10, v10, v254
	v_mul_f32_e32 v11, v11, v255
	v_cvt_pk_bf16_f32 v12, v12, v13
	v_cvt_pk_bf16_f32 v13, v14, v15
	v_cvt_pk_bf16_f32 v14, v8, v9
	v_cvt_pk_bf16_f32 v15, v10, v11
	global_store_dwordx4 v240, v[12:15], s[12:13] nt
	v_mul_f32_e32 v248, 0xbfb8aa3b, v4
	v_mul_f32_e32 v249, 0xbfb8aa3b, v5
	v_mul_f32_e32 v250, 0xbfb8aa3b, v6
	v_mul_f32_e32 v251, 0xbfb8aa3b, v7
	v_mul_f32_e32 v252, 0xbfb8aa3b, v0
	v_mul_f32_e32 v253, 0xbfb8aa3b, v1
	v_mul_f32_e32 v254, 0xbfb8aa3b, v2
	v_mul_f32_e32 v255, 0xbfb8aa3b, v3
	v_exp_f32_e32 v248, v248
	v_exp_f32_e32 v249, v249
	v_exp_f32_e32 v250, v250
	v_exp_f32_e32 v251, v251
	v_exp_f32_e32 v252, v252
	v_exp_f32_e32 v253, v253
	v_exp_f32_e32 v254, v254
	v_exp_f32_e32 v255, v255
	v_add_f32_e32 v248, 1.0, v248
	v_add_f32_e32 v249, 1.0, v249
	v_add_f32_e32 v250, 1.0, v250
	v_add_f32_e32 v251, 1.0, v251
	v_add_f32_e32 v252, 1.0, v252
	v_add_f32_e32 v253, 1.0, v253
	v_add_f32_e32 v254, 1.0, v254
	v_add_f32_e32 v255, 1.0, v255
	v_rcp_f32_e32 v248, v248
	v_rcp_f32_e32 v249, v249
	v_rcp_f32_e32 v250, v250
	v_rcp_f32_e32 v251, v251
	v_rcp_f32_e32 v252, v252
	v_rcp_f32_e32 v253, v253
	v_rcp_f32_e32 v254, v254
	v_rcp_f32_e32 v255, v255
	v_mul_f32_e32 v4, v4, v248
	v_mul_f32_e32 v5, v5, v249
	v_mul_f32_e32 v6, v6, v250
	v_mul_f32_e32 v7, v7, v251
	v_mul_f32_e32 v0, v0, v252
	v_mul_f32_e32 v1, v1, v253
	v_mul_f32_e32 v2, v2, v254
	v_mul_f32_e32 v3, v3, v255
	v_cvt_pk_bf16_f32 v4, v4, v5
	v_cvt_pk_bf16_f32 v5, v6, v7
	v_cvt_pk_bf16_f32 v6, v0, v1
	v_cvt_pk_bf16_f32 v7, v2, v3
	global_store_dwordx4 v240, v[4:7], s[12:13] offset:1024 nt
	s_branch .Lfe_join
.Lfe_gf_sig:
	v_mul_f32_e32 v248, 0xbfb8aa3b, v124
	v_mul_f32_e32 v249, 0xbfb8aa3b, v125
	v_mul_f32_e32 v250, 0xbfb8aa3b, v126
	v_mul_f32_e32 v251, 0xbfb8aa3b, v127
	v_mul_f32_e32 v252, 0xbfb8aa3b, v120
	v_mul_f32_e32 v253, 0xbfb8aa3b, v121
	v_mul_f32_e32 v254, 0xbfb8aa3b, v122
	v_mul_f32_e32 v255, 0xbfb8aa3b, v123
	v_exp_f32_e32 v248, v248
	v_exp_f32_e32 v249, v249
	v_exp_f32_e32 v250, v250
	v_exp_f32_e32 v251, v251
	v_exp_f32_e32 v252, v252
	v_exp_f32_e32 v253, v253
	v_exp_f32_e32 v254, v254
	v_exp_f32_e32 v255, v255
	v_add_f32_e32 v124, 1.0, v248
	v_add_f32_e32 v125, 1.0, v249
	v_add_f32_e32 v126, 1.0, v250
	v_add_f32_e32 v127, 1.0, v251
	v_add_f32_e32 v120, 1.0, v252
	v_add_f32_e32 v121, 1.0, v253
	v_add_f32_e32 v122, 1.0, v254
	v_add_f32_e32 v123, 1.0, v255
	v_cvt_pk_bf16_f32 v124, v124, v125
	v_cvt_pk_bf16_f32 v125, v126, v127
	v_cvt_pk_bf16_f32 v126, v120, v121
	v_cvt_pk_bf16_f32 v127, v122, v123
	global_store_dwordx4 v240, v[124:127], s[12:13] nt
	v_mul_f32_e32 v248, 0xbfb8aa3b, v116
	v_mul_f32_e32 v249, 0xbfb8aa3b, v117
	v_mul_f32_e32 v250, 0xbfb8aa3b, v118
	v_mul_f32_e32 v251, 0xbfb8aa3b, v119
	v_mul_f32_e32 v252, 0xbfb8aa3b, v112
	v_mul_f32_e32 v253, 0xbfb8aa3b, v113
	v_mul_f32_e32 v254, 0xbfb8aa3b, v114
	v_mul_f32_e32 v255, 0xbfb8aa3b, v115
	v_exp_f32_e32 v248, v248
	v_exp_f32_e32 v249, v249
	v_exp_f32_e32 v250, v250
	v_exp_f32_e32 v251, v251
	v_exp_f32_e32 v252, v252
	v_exp_f32_e32 v253, v253
	v_exp_f32_e32 v254, v254
	v_exp_f32_e32 v255, v255
	v_add_f32_e32 v116, 1.0, v248
	v_add_f32_e32 v117, 1.0, v249
	v_add_f32_e32 v118, 1.0, v250
	v_add_f32_e32 v119, 1.0, v251
	v_add_f32_e32 v112, 1.0, v252
	v_add_f32_e32 v113, 1.0, v253
	v_add_f32_e32 v114, 1.0, v254
	v_add_f32_e32 v115, 1.0, v255
	v_cvt_pk_bf16_f32 v116, v116, v117
	v_cvt_pk_bf16_f32 v117, v118, v119
	v_cvt_pk_bf16_f32 v118, v112, v113
	v_cvt_pk_bf16_f32 v119, v114, v115
	global_store_dwordx4 v240, v[116:119], s[12:13] offset:1024 nt
	s_add_u32 s12, s12, 0x800
	s_addc_u32 s13, s13, 0
	v_mul_f32_e32 v248, 0xbfb8aa3b, v108
	v_mul_f32_e32 v249, 0xbfb8aa3b, v109
	v_mul_f32_e32 v250, 0xbfb8aa3b, v110
	v_mul_f32_e32 v251, 0xbfb8aa3b, v111
	v_mul_f32_e32 v252, 0xbfb8aa3b, v104
	v_mul_f32_e32 v253, 0xbfb8aa3b, v105
	v_mul_f32_e32 v254, 0xbfb8aa3b, v106
	v_mul_f32_e32 v255, 0xbfb8aa3b, v107
	v_exp_f32_e32 v248, v248
	v_exp_f32_e32 v249, v249
	v_exp_f32_e32 v250, v250
	v_exp_f32_e32 v251, v251
	v_exp_f32_e32 v252, v252
	v_exp_f32_e32 v253, v253
	v_exp_f32_e32 v254, v254
	v_exp_f32_e32 v255, v255
	v_add_f32_e32 v108, 1.0, v248
	v_add_f32_e32 v109, 1.0, v249
	v_add_f32_e32 v110, 1.0, v250
	v_add_f32_e32 v111, 1.0, v251
	v_add_f32_e32 v104, 1.0, v252
	v_add_f32_e32 v105, 1.0, v253
	v_add_f32_e32 v106, 1.0, v254
	v_add_f32_e32 v107, 1.0, v255
	v_cvt_pk_bf16_f32 v108, v108, v109
	v_cvt_pk_bf16_f32 v109, v110, v111
	v_cvt_pk_bf16_f32 v110, v104, v105
	v_cvt_pk_bf16_f32 v111, v106, v107
	global_store_dwordx4 v240, v[108:111], s[12:13] nt
	v_mul_f32_e32 v248, 0xbfb8aa3b, v100
	v_mul_f32_e32 v249, 0xbfb8aa3b, v101
	v_mul_f32_e32 v250, 0xbfb8aa3b, v102
	v_mul_f32_e32 v251, 0xbfb8aa3b, v103
	v_mul_f32_e32 v252, 0xbfb8aa3b, v96
	v_mul_f32_e32 v253, 0xbfb8aa3b, v97
	v_mul_f32_e32 v254, 0xbfb8aa3b, v98
	v_mul_f32_e32 v255, 0xbfb8aa3b, v99
	v_exp_f32_e32 v248, v248
	v_exp_f32_e32 v249, v249
	v_exp_f32_e32 v250, v250
	v_exp_f32_e32 v251, v251
	v_exp_f32_e32 v252, v252
	v_exp_f32_e32 v253, v253
	v_exp_f32_e32 v254, v254
	v_exp_f32_e32 v255, v255
	v_add_f32_e32 v100, 1.0, v248
	v_add_f32_e32 v101, 1.0, v249
	v_add_f32_e32 v102, 1.0, v250
	v_add_f32_e32 v103, 1.0, v251
	v_add_f32_e32 v96, 1.0, v252
	v_add_f32_e32 v97, 1.0, v253
	v_add_f32_e32 v98, 1.0, v254
	v_add_f32_e32 v99, 1.0, v255
	v_cvt_pk_bf16_f32 v100, v100, v101
	v_cvt_pk_bf16_f32 v101, v102, v103
	v_cvt_pk_bf16_f32 v102, v96, v97
	v_cvt_pk_bf16_f32 v103, v98, v99
	global_store_dwordx4 v240, v[100:103], s[12:13] offset:1024 nt
	s_add_u32 s12, s12, 0x800
	s_addc_u32 s13, s13, 0
	v_mul_f32_e32 v248, 0xbfb8aa3b, v92
	v_mul_f32_e32 v249, 0xbfb8aa3b, v93
	v_mul_f32_e32 v250, 0xbfb8aa3b, v94
	v_mul_f32_e32 v251, 0xbfb8aa3b, v95
	v_mul_f32_e32 v252, 0xbfb8aa3b, v88
	v_mul_f32_e32 v253, 0xbfb8aa3b, v89
	v_mul_f32_e32 v254, 0xbfb8aa3b, v90
	v_mul_f32_e32 v255, 0xbfb8aa3b, v91
	v_exp_f32_e32 v248, v248
	v_exp_f32_e32 v249, v249
	v_exp_f32_e32 v250, v250
	v_exp_f32_e32 v251, v251
	v_exp_f32_e32 v252, v252
	v_exp_f32_e32 v253, v253
	v_exp_f32_e32 v254, v254
	v_exp_f32_e32 v255, v255
	v_add_f32_e32 v92, 1.0, v248
	v_add_f32_e32 v93, 1.0, v249
	v_add_f32_e32 v94, 1.0, v250
	v_add_f32_e32 v95, 1.0, v251
	v_add_f32_e32 v88, 1.0, v252
	v_add_f32_e32 v89, 1.0, v253
	v_add_f32_e32 v90, 1.0, v254
	v_add_f32_e32 v91, 1.0, v255
	v_cvt_pk_bf16_f32 v92, v92, v93
	v_cvt_pk_bf16_f32 v93, v94, v95
	v_cvt_pk_bf16_f32 v94, v88, v89
	v_cvt_pk_bf16_f32 v95, v90, v91
	global_store_dwordx4 v240, v[92:95], s[12:13] nt
	v_mul_f32_e32 v248, 0xbfb8aa3b, v84
	v_mul_f32_e32 v249, 0xbfb8aa3b, v85
	v_mul_f32_e32 v250, 0xbfb8aa3b, v86
	v_mul_f32_e32 v251, 0xbfb8aa3b, v87
	v_mul_f32_e32 v252, 0xbfb8aa3b, v80
	v_mul_f32_e32 v253, 0xbfb8aa3b, v81
	v_mul_f32_e32 v254, 0xbfb8aa3b, v82
	v_mul_f32_e32 v255, 0xbfb8aa3b, v83
	v_exp_f32_e32 v248, v248
	v_exp_f32_e32 v249, v249
	v_exp_f32_e32 v250, v250
	v_exp_f32_e32 v251, v251
	v_exp_f32_e32 v252, v252
	v_exp_f32_e32 v253, v253
	v_exp_f32_e32 v254, v254
	v_exp_f32_e32 v255, v255
	v_add_f32_e32 v84, 1.0, v248
	v_add_f32_e32 v85, 1.0, v249
	v_add_f32_e32 v86, 1.0, v250
	v_add_f32_e32 v87, 1.0, v251
	v_add_f32_e32 v80, 1.0, v252
	v_add_f32_e32 v81, 1.0, v253
	v_add_f32_e32 v82, 1.0, v254
	v_add_f32_e32 v83, 1.0, v255
	v_cvt_pk_bf16_f32 v84, v84, v85
	v_cvt_pk_bf16_f32 v85, v86, v87
	v_cvt_pk_bf16_f32 v86, v80, v81
	v_cvt_pk_bf16_f32 v87, v82, v83
	global_store_dwordx4 v240, v[84:87], s[12:13] offset:1024 nt
	s_add_u32 s12, s12, 0x800
	s_addc_u32 s13, s13, 0
	v_mul_f32_e32 v248, 0xbfb8aa3b, v76
	v_mul_f32_e32 v249, 0xbfb8aa3b, v77
	v_mul_f32_e32 v250, 0xbfb8aa3b, v78
	v_mul_f32_e32 v251, 0xbfb8aa3b, v79
	v_mul_f32_e32 v252, 0xbfb8aa3b, v72
	v_mul_f32_e32 v253, 0xbfb8aa3b, v73
	v_mul_f32_e32 v254, 0xbfb8aa3b, v74
	v_mul_f32_e32 v255, 0xbfb8aa3b, v75
	v_exp_f32_e32 v248, v248
	v_exp_f32_e32 v249, v249
	v_exp_f32_e32 v250, v250
	v_exp_f32_e32 v251, v251
	v_exp_f32_e32 v252, v252
	v_exp_f32_e32 v253, v253
	v_exp_f32_e32 v254, v254
	v_exp_f32_e32 v255, v255
	v_add_f32_e32 v76, 1.0, v248
	v_add_f32_e32 v77, 1.0, v249
	v_add_f32_e32 v78, 1.0, v250
	v_add_f32_e32 v79, 1.0, v251
	v_add_f32_e32 v72, 1.0, v252
	v_add_f32_e32 v73, 1.0, v253
	v_add_f32_e32 v74, 1.0, v254
	v_add_f32_e32 v75, 1.0, v255
	v_cvt_pk_bf16_f32 v76, v76, v77
	v_cvt_pk_bf16_f32 v77, v78, v79
	v_cvt_pk_bf16_f32 v78, v72, v73
	v_cvt_pk_bf16_f32 v79, v74, v75
	global_store_dwordx4 v240, v[76:79], s[12:13] nt
	v_mul_f32_e32 v248, 0xbfb8aa3b, v68
	v_mul_f32_e32 v249, 0xbfb8aa3b, v69
	v_mul_f32_e32 v250, 0xbfb8aa3b, v70
	v_mul_f32_e32 v251, 0xbfb8aa3b, v71
	v_mul_f32_e32 v252, 0xbfb8aa3b, v64
	v_mul_f32_e32 v253, 0xbfb8aa3b, v65
	v_mul_f32_e32 v254, 0xbfb8aa3b, v66
	v_mul_f32_e32 v255, 0xbfb8aa3b, v67
	v_exp_f32_e32 v248, v248
	v_exp_f32_e32 v249, v249
	v_exp_f32_e32 v250, v250
	v_exp_f32_e32 v251, v251
	v_exp_f32_e32 v252, v252
	v_exp_f32_e32 v253, v253
	v_exp_f32_e32 v254, v254
	v_exp_f32_e32 v255, v255
	v_add_f32_e32 v68, 1.0, v248
	v_add_f32_e32 v69, 1.0, v249
	v_add_f32_e32 v70, 1.0, v250
	v_add_f32_e32 v71, 1.0, v251
	v_add_f32_e32 v64, 1.0, v252
	v_add_f32_e32 v65, 1.0, v253
	v_add_f32_e32 v66, 1.0, v254
	v_add_f32_e32 v67, 1.0, v255
	v_cvt_pk_bf16_f32 v68, v68, v69
	v_cvt_pk_bf16_f32 v69, v70, v71
	v_cvt_pk_bf16_f32 v70, v64, v65
	v_cvt_pk_bf16_f32 v71, v66, v67
	global_store_dwordx4 v240, v[68:71], s[12:13] offset:1024 nt
	s_add_u32 s12, s12, 0x800
	s_addc_u32 s13, s13, 0
	v_mul_f32_e32 v248, 0xbfb8aa3b, v60
	v_mul_f32_e32 v249, 0xbfb8aa3b, v61
	v_mul_f32_e32 v250, 0xbfb8aa3b, v62
	v_mul_f32_e32 v251, 0xbfb8aa3b, v63
	v_mul_f32_e32 v252, 0xbfb8aa3b, v56
	v_mul_f32_e32 v253, 0xbfb8aa3b, v57
	v_mul_f32_e32 v254, 0xbfb8aa3b, v58
	v_mul_f32_e32 v255, 0xbfb8aa3b, v59
	v_exp_f32_e32 v248, v248
	v_exp_f32_e32 v249, v249
	v_exp_f32_e32 v250, v250
	v_exp_f32_e32 v251, v251
	v_exp_f32_e32 v252, v252
	v_exp_f32_e32 v253, v253
	v_exp_f32_e32 v254, v254
	v_exp_f32_e32 v255, v255
	v_add_f32_e32 v60, 1.0, v248
	v_add_f32_e32 v61, 1.0, v249
	v_add_f32_e32 v62, 1.0, v250
	v_add_f32_e32 v63, 1.0, v251
	v_add_f32_e32 v56, 1.0, v252
	v_add_f32_e32 v57, 1.0, v253
	v_add_f32_e32 v58, 1.0, v254
	v_add_f32_e32 v59, 1.0, v255
	v_cvt_pk_bf16_f32 v60, v60, v61
	v_cvt_pk_bf16_f32 v61, v62, v63
	v_cvt_pk_bf16_f32 v62, v56, v57
	v_cvt_pk_bf16_f32 v63, v58, v59
	global_store_dwordx4 v240, v[60:63], s[12:13] nt
	v_mul_f32_e32 v248, 0xbfb8aa3b, v52
	v_mul_f32_e32 v249, 0xbfb8aa3b, v53
	v_mul_f32_e32 v250, 0xbfb8aa3b, v54
	v_mul_f32_e32 v251, 0xbfb8aa3b, v55
	v_mul_f32_e32 v252, 0xbfb8aa3b, v48
	v_mul_f32_e32 v253, 0xbfb8aa3b, v49
	v_mul_f32_e32 v254, 0xbfb8aa3b, v50
	v_mul_f32_e32 v255, 0xbfb8aa3b, v51
	v_exp_f32_e32 v248, v248
	v_exp_f32_e32 v249, v249
	v_exp_f32_e32 v250, v250
	v_exp_f32_e32 v251, v251
	v_exp_f32_e32 v252, v252
	v_exp_f32_e32 v253, v253
	v_exp_f32_e32 v254, v254
	v_exp_f32_e32 v255, v255
	v_add_f32_e32 v52, 1.0, v248
	v_add_f32_e32 v53, 1.0, v249
	v_add_f32_e32 v54, 1.0, v250
	v_add_f32_e32 v55, 1.0, v251
	v_add_f32_e32 v48, 1.0, v252
	v_add_f32_e32 v49, 1.0, v253
	v_add_f32_e32 v50, 1.0, v254
	v_add_f32_e32 v51, 1.0, v255
	v_cvt_pk_bf16_f32 v52, v52, v53
	v_cvt_pk_bf16_f32 v53, v54, v55
	v_cvt_pk_bf16_f32 v54, v48, v49
	v_cvt_pk_bf16_f32 v55, v50, v51
	global_store_dwordx4 v240, v[52:55], s[12:13] offset:1024 nt
	s_add_u32 s12, s12, 0x800
	s_addc_u32 s13, s13, 0
	v_mul_f32_e32 v248, 0xbfb8aa3b, v44
	v_mul_f32_e32 v249, 0xbfb8aa3b, v45
	v_mul_f32_e32 v250, 0xbfb8aa3b, v46
	v_mul_f32_e32 v251, 0xbfb8aa3b, v47
	v_mul_f32_e32 v252, 0xbfb8aa3b, v40
	v_mul_f32_e32 v253, 0xbfb8aa3b, v41
	v_mul_f32_e32 v254, 0xbfb8aa3b, v42
	v_mul_f32_e32 v255, 0xbfb8aa3b, v43
	v_exp_f32_e32 v248, v248
	v_exp_f32_e32 v249, v249
	v_exp_f32_e32 v250, v250
	v_exp_f32_e32 v251, v251
	v_exp_f32_e32 v252, v252
	v_exp_f32_e32 v253, v253
	v_exp_f32_e32 v254, v254
	v_exp_f32_e32 v255, v255
	v_add_f32_e32 v44, 1.0, v248
	v_add_f32_e32 v45, 1.0, v249
	v_add_f32_e32 v46, 1.0, v250
	v_add_f32_e32 v47, 1.0, v251
	v_add_f32_e32 v40, 1.0, v252
	v_add_f32_e32 v41, 1.0, v253
	v_add_f32_e32 v42, 1.0, v254
	v_add_f32_e32 v43, 1.0, v255
	v_cvt_pk_bf16_f32 v44, v44, v45
	v_cvt_pk_bf16_f32 v45, v46, v47
	v_cvt_pk_bf16_f32 v46, v40, v41
	v_cvt_pk_bf16_f32 v47, v42, v43
	global_store_dwordx4 v240, v[44:47], s[12:13] nt
	v_mul_f32_e32 v248, 0xbfb8aa3b, v36
	v_mul_f32_e32 v249, 0xbfb8aa3b, v37
	v_mul_f32_e32 v250, 0xbfb8aa3b, v38
	v_mul_f32_e32 v251, 0xbfb8aa3b, v39
	v_mul_f32_e32 v252, 0xbfb8aa3b, v32
	v_mul_f32_e32 v253, 0xbfb8aa3b, v33
	v_mul_f32_e32 v254, 0xbfb8aa3b, v34
	v_mul_f32_e32 v255, 0xbfb8aa3b, v35
	v_exp_f32_e32 v248, v248
	v_exp_f32_e32 v249, v249
	v_exp_f32_e32 v250, v250
	v_exp_f32_e32 v251, v251
	v_exp_f32_e32 v252, v252
	v_exp_f32_e32 v253, v253
	v_exp_f32_e32 v254, v254
	v_exp_f32_e32 v255, v255
	v_add_f32_e32 v36, 1.0, v248
	v_add_f32_e32 v37, 1.0, v249
	v_add_f32_e32 v38, 1.0, v250
	v_add_f32_e32 v39, 1.0, v251
	v_add_f32_e32 v32, 1.0, v252
	v_add_f32_e32 v33, 1.0, v253
	v_add_f32_e32 v34, 1.0, v254
	v_add_f32_e32 v35, 1.0, v255
	v_cvt_pk_bf16_f32 v36, v36, v37
	v_cvt_pk_bf16_f32 v37, v38, v39
	v_cvt_pk_bf16_f32 v38, v32, v33
	v_cvt_pk_bf16_f32 v39, v34, v35
	global_store_dwordx4 v240, v[36:39], s[12:13] offset:1024 nt
	s_add_u32 s12, s12, 0x800
	s_addc_u32 s13, s13, 0
	v_mul_f32_e32 v248, 0xbfb8aa3b, v28
	v_mul_f32_e32 v249, 0xbfb8aa3b, v29
	v_mul_f32_e32 v250, 0xbfb8aa3b, v30
	v_mul_f32_e32 v251, 0xbfb8aa3b, v31
	v_mul_f32_e32 v252, 0xbfb8aa3b, v24
	v_mul_f32_e32 v253, 0xbfb8aa3b, v25
	v_mul_f32_e32 v254, 0xbfb8aa3b, v26
	v_mul_f32_e32 v255, 0xbfb8aa3b, v27
	v_exp_f32_e32 v248, v248
	v_exp_f32_e32 v249, v249
	v_exp_f32_e32 v250, v250
	v_exp_f32_e32 v251, v251
	v_exp_f32_e32 v252, v252
	v_exp_f32_e32 v253, v253
	v_exp_f32_e32 v254, v254
	v_exp_f32_e32 v255, v255
	v_add_f32_e32 v28, 1.0, v248
	v_add_f32_e32 v29, 1.0, v249
	v_add_f32_e32 v30, 1.0, v250
	v_add_f32_e32 v31, 1.0, v251
	v_add_f32_e32 v24, 1.0, v252
	v_add_f32_e32 v25, 1.0, v253
	v_add_f32_e32 v26, 1.0, v254
	v_add_f32_e32 v27, 1.0, v255
	v_cvt_pk_bf16_f32 v28, v28, v29
	v_cvt_pk_bf16_f32 v29, v30, v31
	v_cvt_pk_bf16_f32 v30, v24, v25
	v_cvt_pk_bf16_f32 v31, v26, v27
	global_store_dwordx4 v240, v[28:31], s[12:13] nt
	v_mul_f32_e32 v248, 0xbfb8aa3b, v20
	v_mul_f32_e32 v249, 0xbfb8aa3b, v21
	v_mul_f32_e32 v250, 0xbfb8aa3b, v22
	v_mul_f32_e32 v251, 0xbfb8aa3b, v23
	v_mul_f32_e32 v252, 0xbfb8aa3b, v16
	v_mul_f32_e32 v253, 0xbfb8aa3b, v17
	v_mul_f32_e32 v254, 0xbfb8aa3b, v18
	v_mul_f32_e32 v255, 0xbfb8aa3b, v19
	v_exp_f32_e32 v248, v248
	v_exp_f32_e32 v249, v249
	v_exp_f32_e32 v250, v250
	v_exp_f32_e32 v251, v251
	v_exp_f32_e32 v252, v252
	v_exp_f32_e32 v253, v253
	v_exp_f32_e32 v254, v254
	v_exp_f32_e32 v255, v255
	v_add_f32_e32 v20, 1.0, v248
	v_add_f32_e32 v21, 1.0, v249
	v_add_f32_e32 v22, 1.0, v250
	v_add_f32_e32 v23, 1.0, v251
	v_add_f32_e32 v16, 1.0, v252
	v_add_f32_e32 v17, 1.0, v253
	v_add_f32_e32 v18, 1.0, v254
	v_add_f32_e32 v19, 1.0, v255
	v_cvt_pk_bf16_f32 v20, v20, v21
	v_cvt_pk_bf16_f32 v21, v22, v23
	v_cvt_pk_bf16_f32 v22, v16, v17
	v_cvt_pk_bf16_f32 v23, v18, v19
	global_store_dwordx4 v240, v[20:23], s[12:13] offset:1024 nt
	s_add_u32 s12, s12, 0x800
	s_addc_u32 s13, s13, 0
	v_mul_f32_e32 v248, 0xbfb8aa3b, v12
	v_mul_f32_e32 v249, 0xbfb8aa3b, v13
	v_mul_f32_e32 v250, 0xbfb8aa3b, v14
	v_mul_f32_e32 v251, 0xbfb8aa3b, v15
	v_mul_f32_e32 v252, 0xbfb8aa3b, v8
	v_mul_f32_e32 v253, 0xbfb8aa3b, v9
	v_mul_f32_e32 v254, 0xbfb8aa3b, v10
	v_mul_f32_e32 v255, 0xbfb8aa3b, v11
	v_exp_f32_e32 v248, v248
	v_exp_f32_e32 v249, v249
	v_exp_f32_e32 v250, v250
	v_exp_f32_e32 v251, v251
	v_exp_f32_e32 v252, v252
	v_exp_f32_e32 v253, v253
	v_exp_f32_e32 v254, v254
	v_exp_f32_e32 v255, v255
	v_add_f32_e32 v12, 1.0, v248
	v_add_f32_e32 v13, 1.0, v249
	v_add_f32_e32 v14, 1.0, v250
	v_add_f32_e32 v15, 1.0, v251
	v_add_f32_e32 v8, 1.0, v252
	v_add_f32_e32 v9, 1.0, v253
	v_add_f32_e32 v10, 1.0, v254
	v_add_f32_e32 v11, 1.0, v255
	v_cvt_pk_bf16_f32 v12, v12, v13
	v_cvt_pk_bf16_f32 v13, v14, v15
	v_cvt_pk_bf16_f32 v14, v8, v9
	v_cvt_pk_bf16_f32 v15, v10, v11
	global_store_dwordx4 v240, v[12:15], s[12:13] nt
	v_mul_f32_e32 v248, 0xbfb8aa3b, v4
	v_mul_f32_e32 v249, 0xbfb8aa3b, v5
	v_mul_f32_e32 v250, 0xbfb8aa3b, v6
	v_mul_f32_e32 v251, 0xbfb8aa3b, v7
	v_mul_f32_e32 v252, 0xbfb8aa3b, v0
	v_mul_f32_e32 v253, 0xbfb8aa3b, v1
	v_mul_f32_e32 v254, 0xbfb8aa3b, v2
	v_mul_f32_e32 v255, 0xbfb8aa3b, v3
	v_exp_f32_e32 v248, v248
	v_exp_f32_e32 v249, v249
	v_exp_f32_e32 v250, v250
	v_exp_f32_e32 v251, v251
	v_exp_f32_e32 v252, v252
	v_exp_f32_e32 v253, v253
	v_exp_f32_e32 v254, v254
	v_exp_f32_e32 v255, v255
	v_add_f32_e32 v4, 1.0, v248
	v_add_f32_e32 v5, 1.0, v249
	v_add_f32_e32 v6, 1.0, v250
	v_add_f32_e32 v7, 1.0, v251
	v_add_f32_e32 v0, 1.0, v252
	v_add_f32_e32 v1, 1.0, v253
	v_add_f32_e32 v2, 1.0, v254
	v_add_f32_e32 v3, 1.0, v255
	v_cvt_pk_bf16_f32 v4, v4, v5
	v_cvt_pk_bf16_f32 v5, v6, v7
	v_cvt_pk_bf16_f32 v6, v0, v1
	v_cvt_pk_bf16_f32 v7, v2, v3
	global_store_dwordx4 v240, v[4:7], s[12:13] offset:1024 nt
